# NA attention: tile loop duplicated by wave parity (query columns 0-31 / 32-63); score elements outside every window of that parity skip bias lookup, select, exp, convert and their all-zero PV/row-sum
# baseline (speedup 1.0000x reference)
; #define LAS __attribute__((address_space(3)))
; template <int KIND> ...
;     ...
;         int base1 = b * 4096, n1 = 64, kr_lo = 0, rs_w = 0, qr = 0, qc = 0, cs = 0;
;         if (KIND == 0) { const int r0 = qb * 4; kr_lo = min(max(r0 - 4, 0), 56); const int kr_hi = min(max(r0 - 1, 0), 56) + 8; base1 += kr_lo * 64; n1 = kr_hi - kr_lo;
;             qr = r0 + (wid >> 1); rs_w = min(max(qr - 4, 0), 56); qc = 32 * (wid & 1) + l32; cs = min(max(qc - 8, 0), 48); }
;         if (isctx) n1 = 0;
;         const int base2 = M_LAT + b * 256, nt = n1 + 4;
;         bf16x8 qf[4];
;         { const bf16_t* qp = qkv + (size_t)(qrow0 + qoff + l32) * N + hq * 64 + 8 * hi;
; #pragma unroll
;           for (int t = 0; t < 4; ++t) qf[t] = *(const bf16x8*)(qp + 16 * t); }
;         if (KIND == 0 && !isctx) { LAS float* bt = (LAS float*)(lds + OFF_BIAS); for (int i = tid; i < 465; i += NTHREADS) bt[i] = rpb[h * 465 + i] * LOG2E; }
;         u32x4 kreg[NK], vreg[NVC];
;         const int krow_l = tid >> 3, kpart = tid & 7;
;     ...
;         float m_ref = 0.f; int first = 1;
;         f32x16 o[NDT], lacc, mneg;
; #pragma unroll
;         for (int dt = 0; dt < NDT; ++dt)
; #pragma unroll
;             for (int j = 0; j < 16; ++j) o[dt][j] = 0.f;
; #pragma unroll
;         for (int j = 0; j < 16; ++j) { lacc[j] = 0.f; mneg[j] = 0.f; }
;         const bf16x8 ones = {(short)0x3F80, (short)0x3F80, (short)0x3F80, (short)0x3F80, (short)0x3F80, (short)0x3F80, (short)0x3F80, (short)0x3F80};
;         ATT_LOAD(0); ATT_STORE(0); __syncthreads();
;         const int koff = kidx * KT + l32 * KSTR + 16 * hi;
;         const int voff = OFF_V + (4 * hi + ((lane & 15) >> 2)) * VSTR + (16 * ((lane >> 4) & 1) + 4 * (lane & 3)) * 2;
;         const int wb = 4 * hi - cs;
.LBB0_143:
	s_or_b64 exec, exec, s[82:83]
	s_lshl_b32 s75, s81, 2
	v_sub_u32_e64 v0, s75, 1 clamp
	s_max_u32 s90, s75, 4
	v_readfirstlane_b32 s10, v0
	s_min_u32 s10, s10, 56
	s_lshl_b32 s8, s74, 6
	s_lshl_b32 s2, s2, 8
	s_sub_i32 s10, s10, s90
	s_add_i32 s9, s8, 0x800
	s_add_i32 s2, s2, 0x8000
	s_add_i32 s10, s10, 12
	s_and_b64 s[76:77], exec, s[78:79]
	s_cselect_b32 s80, 0, s10
	s_lshl_b32 s10, s80, 6
	v_sub_u32_e64 v4, s75, 4 clamp
	s_sub_i32 s10, s2, s10
	v_lshlrev_b32_e32 v0, 6, v4
	s_cmp_gt_i32 s80, 0
	v_add_u32_e32 v0, s5, v0
	v_mov_b32_e32 v1, s10
	s_cselect_b64 vcc, -1, 0
	v_readlane_b32 s10, v255, 5
	v_cndmask_b32_e32 v5, v1, v0, vcc
	v_readlane_b32 s11, v255, 6
	v_add_u32_e32 v2, v5, v208
	v_add_u32_e32 v5, v5, v209
	v_mov_b64_e32 v[0:1], s[10:11]
	s_movk_i32 s10, 0x1800
	v_mad_i64_i32 v[2:3], s[76:77], v2, s10, v[0:1]
	s_lshl_b32 s96, s8, 1
	v_mad_i64_i32 v[0:1], s[76:77], v5, s10, v[0:1]
	v_lshl_add_u64 v[2:3], v[2:3], 0, s[96:97]
	s_lshl_b32 s76, s9, 1
	s_mov_b32 s77, s97
	v_lshl_add_u64 v[2:3], v[2:3], 0, v[192:193]
	v_lshl_add_u64 v[0:1], v[0:1], 0, s[76:77]
	v_lshl_add_u64 v[0:1], v[154:155], 1, v[0:1]
	global_load_dwordx4 v[128:131], v[2:3], off offset:2048
	global_load_dwordx4 v[132:135], v[0:1], off
	v_readfirstlane_b32 s74, v4
	s_cmp_lt_i32 s80, -3
	s_mov_b32 s83, 0
	s_waitcnt vmcnt(1)
	ds_write_b128 v210, v[128:131]
	s_waitcnt vmcnt(0)
	ds_write_b128 v211, v[132:135] offset:18432
	s_waitcnt lgkmcnt(0)
	s_barrier
	s_cbranch_scc1 .LBB0_166
	v_readlane_b32 s8, v255, 41
	s_add_i32 s75, s75, s8
	s_max_i32 s8, s75, 4
	s_add_i32 s8, s8, -4
	s_min_u32 s75, s8, 56
	s_mulk_i32 s90, 0x7c
	s_mul_i32 s8, s81, 0x1f0
	v_mov_b32_e32 v46, v193
	v_mov_b32_e32 v47, v193
	s_sub_i32 s8, s90, s8
	v_mov_b32_e32 v32, v193
	v_mov_b32_e32 v33, v193
	v_mov_b32_e32 v34, v193
	v_mov_b32_e32 v35, v193
	v_mov_b32_e32 v36, v193
	v_mov_b32_e32 v37, v193
	v_mov_b32_e32 v38, v193
	v_mov_b32_e32 v39, v193
	v_mov_b32_e32 v40, v193
	v_mov_b32_e32 v41, v193
	v_mov_b32_e32 v42, v193
	v_mov_b32_e32 v43, v193
	v_mov_b32_e32 v44, v193
	v_mov_b32_e32 v45, v193
	v_mov_b32_e32 v16, 0
	v_mov_b64_e32 v[62:63], v[46:47]
	s_add_i32 s95, s80, 4
	s_mov_b32 s82, 1
	v_lshl_add_u64 v[202:203], v[156:157], 0, s[96:97]
	v_lshl_add_u64 v[204:205], v[158:159], 0, s[76:77]
	s_add_i32 s76, s75, 8
	s_sub_i32 s77, 0, s80
	v_add_u32_e32 v237, s8, v235
	v_mov_b64_e32 v[60:61], v[44:45]
	v_mov_b64_e32 v[58:59], v[42:43]
	v_mov_b64_e32 v[56:57], v[40:41]
	v_mov_b64_e32 v[54:55], v[38:39]
	v_mov_b64_e32 v[52:53], v[36:37]
	v_mov_b64_e32 v[50:51], v[34:35]
	v_mov_b64_e32 v[48:49], v[32:33]
	v_mov_b32_e32 v17, v16
	v_mov_b32_e32 v18, v16
	v_mov_b32_e32 v19, v16
	v_mov_b32_e32 v20, v16
	v_mov_b32_e32 v21, v16
	v_mov_b32_e32 v22, v16
	v_mov_b32_e32 v23, v16
	v_mov_b32_e32 v24, v16
	v_mov_b32_e32 v25, v16
	v_mov_b32_e32 v26, v16
	v_mov_b32_e32 v27, v16
	v_mov_b32_e32 v28, v16
	v_mov_b32_e32 v29, v16
	v_mov_b32_e32 v30, v16
	v_mov_b32_e32 v31, v16
	v_mov_b32_e32 v0, v16
	v_mov_b32_e32 v1, v16
	v_mov_b32_e32 v2, v16
	v_mov_b32_e32 v3, v16
	v_mov_b32_e32 v4, v16
	v_mov_b32_e32 v5, v16
	v_mov_b32_e32 v6, v16
	v_mov_b32_e32 v7, v16
	v_mov_b32_e32 v8, v16
	v_mov_b32_e32 v9, v16
	v_mov_b32_e32 v10, v16
	v_mov_b32_e32 v11, v16
	v_mov_b32_e32 v12, v16
	v_mov_b32_e32 v13, v16
	v_mov_b32_e32 v14, v16
	v_mov_b32_e32 v15, v16
	v_readlane_b32 s8, v255, 22
	s_nop 0
	s_bitcmp1_b32 s8, 0
	s_cbranch_scc1 nap1_145

; #define LAS __attribute__((address_space(3)))
; template <int KIND> ...
;     ...
;         for (int t = 0; t < nt; ++t) {
;             if (t + 1 < nt) ATT_LOAD(t + 1);
;             bool active = true;
;             if (KIND == 0 && t < n1) { const int kr = kr_lo + t; active = (kr >= rs_w) && (kr < rs_w + 8); }
;             if (__builtin_amdgcn_readfirstlane((int)active)) {
;                 const int buf = t & 1;
;                 bf16x8 kf[8];
; #pragma unroll
;                 for (int t4 = 0; t4 < 4; ++t4) { kf[2 * t4] = *(const LAS bf16x8*)(lds + buf * KBUF + koff + 32 * t4); kf[2 * t4 + 1] = *(const LAS bf16x8*)(lds + buf * KBUF + koff + 32 * KSTR + 32 * t4); }
;                 __builtin_amdgcn_sched_barrier(0);
;                 f32x16 s0, s1;
; #pragma unroll
;                 for (int t4 = 0; t4 < 4; ++t4) {
;                     s0 = __builtin_amdgcn_mfma_f32_32x32x16_bf16(kf[2 * t4], qf[t4], t4 == 0 ? mneg : s0, 0, 0, 0);
;                     s1 = __builtin_amdgcn_mfma_f32_32x32x16_bf16(kf[2 * t4 + 1], qf[t4], t4 == 0 ? mneg : s1, 0, 0, 0);
;                 }
;                 float ab0[16], ab1[16];
;                 const bool na_lat = (KIND == 0) && (t < n1);
;                 if (na_lat) {
;                     const int bo = boff0 + (kr_lo + t - qr + 7) * 124;
; #pragma unroll
;                     for (int j = 0; j < 16; ++j) {
;                         const int C0 = 8 * (j >> 2) + (j & 3), C1 = 32 + C0;
;                         const float b0 = *(const LAS float*)(lds + bo + 4 * C0), b1 = *(const LAS float*)(lds + bo + 4 * C1);
;                         ab0[j] = ((unsigned)(wb + C0) < 16u) ? b0 : -1e30f;
;                         ab1[j] = ((unsigned)(wb + C1) < 16u) ? b1 : -1e30f;
;                     }
; #pragma unroll
;                     for (int i = 0; i < 8; ++i) { __builtin_amdgcn_sched_group_barrier(0x008, 1, 0); __builtin_amdgcn_sched_group_barrier(0x100, 4, 0); __builtin_amdgcn_sched_group_barrier(0x002, 12, 0); }
;                 }
;                 __builtin_amdgcn_sched_barrier(0);
;                 s16x4 vfa[2][NDT][2], vfb[2][NDT][2];
; #pragma unroll
;                 for (int s = 0; s < 2; ++s)
; #pragma unroll
;                     for (int dt = 0; dt < NDT; ++dt) {
;                         vfa[s][dt][0] = __builtin_amdgcn_ds_read_tr16_b64_v4i16((LAS s16x4*)(lds + buf * VBUF + voff + (16 * s) * VSTR + 64 * dt));
.LBB0_147:
	s_cmp_lt_i32 s83, s80
	s_cselect_b64 s[78:79], -1, 0
	s_cmp_ge_i32 s83, s80
	s_cselect_b64 vcc, -1, 0
	s_add_i32 s10, s74, s83
	s_cmp_ge_i32 s10, s75
	s_cselect_b64 s[8:9], -1, 0
	s_cmp_lt_i32 s10, s76
	s_cselect_b64 s[10:11], -1, 0
	s_and_b64 s[8:9], s[8:9], s[10:11]
	s_or_b64 s[8:9], vcc, s[8:9]
	s_cmp_eq_u64 s[8:9], 0
	s_cbranch_scc1 .LBB0_162
	s_and_b32 s83, s83, 1
	s_mul_i32 s8, s83, 0x2400
	v_add_u32_e32 v68, s8, v212
	ds_read_b128 v[64:67], v68
	ds_read_b128 v[80:83], v68 offset:32
	ds_read_b128 v[84:87], v68 offset:4608
	ds_read_b128 v[88:91], v68 offset:4640
	ds_read_b128 v[92:95], v68 offset:64
	ds_read_b128 v[136:139], v68 offset:96
	ds_read_b128 v[140:143], v68 offset:4672
	ds_read_b128 v[144:147], v68 offset:4704
	s_waitcnt lgkmcnt(7)
	v_mfma_f32_32x32x16_bf16 v[96:111], v[64:67], v[112:115], v[48:63]
	s_andn2_b64 vcc, exec, s[78:79]
	s_waitcnt lgkmcnt(5)
	v_mfma_f32_32x32x16_bf16 v[64:79], v[84:87], v[112:115], v[48:63]
	v_mfma_f32_32x32x16_bf16 v[96:111], v[80:83], v[116:119], v[96:111]
	s_waitcnt lgkmcnt(4)
	v_mfma_f32_32x32x16_bf16 v[64:79], v[88:91], v[116:119], v[64:79]
	s_waitcnt lgkmcnt(3)
	v_mfma_f32_32x32x16_bf16 v[96:111], v[92:95], v[120:123], v[96:111]
	s_waitcnt lgkmcnt(1)
	v_mfma_f32_32x32x16_bf16 v[64:79], v[140:143], v[120:123], v[64:79]
	v_mfma_f32_32x32x16_bf16 v[96:111], v[136:139], v[124:127], v[96:111]
	s_waitcnt lgkmcnt(0)
	v_mfma_f32_32x32x16_bf16 v[64:79], v[144:147], v[124:127], v[64:79]
	s_cbranch_vccnz .LBB0_150
	ds_read2_b32 v[80:81], v237 offset0:32 offset1:33
	ds_read2_b32 v[82:83], v237 offset1:1
	ds_read2_b32 v[84:85], v237 offset0:2 offset1:3
	ds_read2_b32 v[86:87], v237 offset0:34 offset1:35
	v_readlane_b32 s8, v255, 33
	v_readlane_b32 s9, v255, 34
	s_waitcnt lgkmcnt(0)
	v_cndmask_b32_e64 v163, v229, v83, s[12:13]
	v_cndmask_b32_e64 v160, v229, v81, s[14:15]
	v_cndmask_b32_e64 v236, v229, v80, s[8:9]
	v_readlane_b32 s8, v255, 35
	v_readlane_b32 s9, v255, 36
	v_cndmask_b32_e64 v165, v229, v85, s[16:17]
	v_cndmask_b32_e64 v164, v229, v84, s[18:19]
	v_cndmask_b32_e64 v162, v229, v82, s[8:9]
	v_cndmask_b32_e64 v167, v229, v87, s[20:21]
	v_cndmask_b32_e64 v166, v229, v86, s[22:23]
	ds_read2_b32 v[80:81], v237 offset0:8 offset1:9
	ds_read2_b32 v[84:85], v237 offset0:10 offset1:11
	s_waitcnt lgkmcnt(0)
	v_cndmask_b32_e64 v171, v229, v81, s[24:25]
	v_cndmask_b32_e64 v170, v229, v80, s[26:27]
	v_cndmask_b32_e64 v175, v229, v85, s[34:35]
	v_cndmask_b32_e64 v174, v229, v84, s[36:37]
	ds_read2_b32 v[82:83], v237 offset0:16 offset1:17
	ds_read2_b32 v[84:85], v237 offset0:18 offset1:19
	s_waitcnt lgkmcnt(0)
	v_cndmask_b32_e64 v183, v229, v83, s[46:47]
	v_cndmask_b32_e64 v182, v229, v82, s[44:45]
	v_cndmask_b32_e64 v185, v229, v85, s[50:51]
	v_cndmask_b32_e64 v184, v229, v84, s[52:53]
	ds_read2_b32 v[80:81], v237 offset0:24 offset1:25
	ds_read2_b32 v[84:85], v237 offset0:26 offset1:27
	s_waitcnt lgkmcnt(0)
	v_cndmask_b32_e64 v189, v229, v81, s[58:59]
	v_cndmask_b32_e64 v188, v229, v80, s[60:61]
	v_cndmask_b32_e64 v201, v229, v85, s[66:67]
	v_cndmask_b32_e64 v200, v229, v84, s[68:69]
.LBB0_150:
	s_mulk_i32 s83, 0x3000
	v_add_u32_e32 v238, s83, v213
	ds_read_b64_tr_b16 v[148:149], v238 offset:18432
	ds_read_b64_tr_b16 v[150:151], v238 offset:19968
	ds_read_b64_tr_b16 v[146:147], v238 offset:20032
	ds_read_b64_tr_b16 v[144:145], v238 offset:18496
	ds_read_b64_tr_b16 v[140:141], v238 offset:21504
	ds_read_b64_tr_b16 v[142:143], v238 offset:23040
	ds_read_b64_tr_b16 v[138:139], v238 offset:23104
	ds_read_b64_tr_b16 v[136:137], v238 offset:21568
	s_and_b64 vcc, exec, s[78:79]
	s_cbranch_vccz .LBB0_152
	v_add_f32_e32 v65, v65, v160
	v_add_f32_e32 v66, v66, v166
	v_add_f32_e32 v67, v67, v167
	v_mov_b32_e32 v68, v229
	v_mov_b32_e32 v69, v229
	v_mov_b32_e32 v70, v229
	v_mov_b32_e32 v71, v229
	v_mov_b32_e32 v72, v229
	v_mov_b32_e32 v73, v229
	v_mov_b32_e32 v74, v229
	v_mov_b32_e32 v75, v229
	v_mov_b32_e32 v76, v229
	v_mov_b32_e32 v77, v229
	v_mov_b32_e32 v78, v229
	v_add_f32_e32 v206, v64, v236
	v_pk_add_f32 v[80:81], v[96:97], v[162:163]
	v_pk_add_f32 v[94:95], v[110:111], v[200:201]
	v_pk_add_f32 v[92:93], v[108:109], v[188:189]
	v_pk_add_f32 v[90:91], v[106:107], v[184:185]
	v_pk_add_f32 v[88:89], v[104:105], v[182:183]
	v_pk_add_f32 v[86:87], v[102:103], v[174:175]
	v_pk_add_f32 v[84:85], v[100:101], v[170:171]
	v_pk_add_f32 v[82:83], v[98:99], v[164:165]
	v_mov_b32_e32 v161, v229
	s_cbranch_execz .LBB0_153
	s_branch .LBB0_154

; template <int KIND> ...
;     ...
; #pragma unroll
;                 for (int j = 0; j < 16; ++j) s0[j] = __builtin_amdgcn_exp2f(s0[j]);
;                 bf16x8 pf[4];
; #pragma unroll
;                 for (int s = 0; s < 2; ++s) { u32x4 w; w.x = pk2n(s0[8 * s + 0], s0[8 * s + 1]); w.y = pk2n(s0[8 * s + 2], s0[8 * s + 3]); w.z = pk2n(s0[8 * s + 4], s0[8 * s + 5]); w.w = pk2n(s0[8 * s + 6], s0[8 * s + 7]);
;                     pf[s] = __builtin_bit_cast(bf16x8, w); }
;                 __builtin_amdgcn_sched_barrier(0);
; #pragma unroll
;                 for (int s = 0; s < 2; ++s)
; #pragma unroll
;                     for (int dt = 0; dt < NDT; ++dt) {
;                         vfb[s][dt][0] = __builtin_amdgcn_ds_read_tr16_b64_v4i16((LAS s16x4*)(lds + buf * VBUF + voff + (16 * (s + 2)) * VSTR + 64 * dt));
;                         vfb[s][dt][1] = __builtin_amdgcn_ds_read_tr16_b64_v4i16((LAS s16x4*)(lds + buf * VBUF + voff + (16 * (s + 2) + 8) * VSTR + 64 * dt)); }
;                 {
;                     constexpr int NM = 2 * (1 + NDT);
;                     int mi = 0;
; #pragma unroll
;                     for (int s = 0; s < 2; ++s) {
;                         lacc = __builtin_amdgcn_mfma_f32_32x32x16_bf16(ones, pf[s], lacc, 0, 0, 0);
; #pragma unroll
;                         for (int j = (mi * 16) / NM; j < ((mi + 1) * 16) / NM; ++j) s1[j] = __builtin_amdgcn_exp2f(s1[j]);
;                         ++mi;
; #pragma unroll
;                         for (int dt = 0; dt < NDT; ++dt) {
;                             const s16x4 va = vfa[s][dt][0], vb = vfa[s][dt][1];
;                             const bf16x8 vf = {va[0], va[1], va[2], va[3], vb[0], vb[1], vb[2], vb[3]};
;                             o[dt] = __builtin_amdgcn_mfma_f32_32x32x16_bf16(vf, pf[s], o[dt], 0, 0, 0);
; #pragma unroll
;                             for (int j = (mi * 16) / NM; j < ((mi + 1) * 16) / NM; ++j) s1[j] = __builtin_amdgcn_exp2f(s1[j]);
;                             ++mi;
;                         }
;                     }
; #pragma unroll
;                     for (int q = 0; q < 2; ++q) { u32x4 w; w.x = pk2n(s1[8 * q + 0], s1[8 * q + 1]); w.y = pk2n(s1[8 * q + 2], s1[8 * q + 3]); w.z = pk2n(s1[8 * q + 4], s1[8 * q + 5]); w.w = pk2n(s1[8 * q + 6], s1[8 * q + 7]);
;                         pf[q + 2] = __builtin_bit_cast(bf16x8, w); }
; #pragma unroll
.LBB0_161:
	s_cmp_le_i32 s81, s80
	s_cbranch_scc0 nap0_ygen
	v_exp_f32_e32 v64, v80
	v_exp_f32_e32 v79, v81
	v_exp_f32_e32 v81, v82
	v_exp_f32_e32 v82, v83
	v_exp_f32_e32 v83, v84
	v_exp_f32_e32 v84, v85
	v_exp_f32_e32 v85, v86
	v_exp_f32_e32 v86, v87
	v_exp_f32_e32 v87, v88
	v_exp_f32_e32 v88, v89
	v_exp_f32_e32 v89, v90
	v_exp_f32_e32 v90, v91
	v_exp_f32_e32 v91, v92
	v_exp_f32_e32 v92, v93
	v_exp_f32_e32 v93, v94
	v_exp_f32_e32 v94, v95
	v_cvt_pk_bf16_f32 v80, v64, v79
	v_cvt_pk_bf16_f32 v81, v81, v82
	v_cvt_pk_bf16_f32 v82, v83, v84
	v_cvt_pk_bf16_f32 v83, v85, v86
	v_cvt_pk_bf16_f32 v84, v87, v88
	v_cvt_pk_bf16_f32 v85, v89, v90
	v_cvt_pk_bf16_f32 v86, v91, v92
	v_cvt_pk_bf16_f32 v87, v93, v94
	s_waitcnt lgkmcnt(6)
	v_mfma_f32_32x32x16_bf16 v[16:31], v[148:151], v[80:83], v[16:31]
	v_mov_b64_e32 v[90:91], s[86:87]
	v_mov_b64_e32 v[88:89], s[84:85]
	v_exp_f32_e32 v92, v206
	v_exp_f32_e32 v93, v65
	ds_read_b64_tr_b16 v[64:65], v238 offset:24576
	v_mfma_f32_32x32x16_bf16 v[32:47], v[88:91], v[80:83], v[32:47]
	v_exp_f32_e32 v94, v66
	v_exp_f32_e32 v95, v67
	ds_read_b64_tr_b16 v[66:67], v238 offset:26112
	ds_read_b64_tr_b16 v[68:69], v238 offset:24640
	s_waitcnt lgkmcnt(7)
	v_mfma_f32_32x32x16_bf16 v[0:15], v[144:147], v[80:83], v[0:15]
	ds_read_b64_tr_b16 v[70:71], v238 offset:26176
	ds_read_b64_tr_b16 v[72:73], v238 offset:27648
	v_mfma_f32_32x32x16_bf16 v[32:47], v[88:91], v[84:87], v[32:47]
	ds_read_b64_tr_b16 v[74:75], v238 offset:29184
	ds_read_b64_tr_b16 v[76:77], v238 offset:27712
	s_waitcnt lgkmcnt(9)
	v_mfma_f32_32x32x16_bf16 v[16:31], v[140:143], v[84:87], v[16:31]
	v_cvt_pk_bf16_f32 v80, v92, v93
	v_cvt_pk_bf16_f32 v81, v94, v95
	ds_read_b64_tr_b16 v[78:79], v238 offset:29248
	s_waitcnt lgkmcnt(8)
	v_mfma_f32_32x32x16_bf16 v[0:15], v[136:139], v[84:87], v[0:15]
	v_mov_b32_e32 v82, 0
	v_mov_b32_e32 v83, 0
	v_mov_b32_e32 v84, 0
	v_mov_b32_e32 v85, 0
	v_mov_b32_e32 v86, 0
	v_mov_b32_e32 v87, 0
	s_waitcnt lgkmcnt(6)
	v_mfma_f32_32x32x16_bf16 v[16:31], v[64:67], v[80:83], v[16:31]
	s_waitcnt lgkmcnt(4)
	v_mfma_f32_32x32x16_bf16 v[0:15], v[68:71], v[80:83], v[0:15]
	v_mfma_f32_32x32x16_bf16 v[32:47], v[88:91], v[80:83], v[32:47]
	s_waitcnt lgkmcnt(2)
	s_waitcnt lgkmcnt(0)
	s_mov_b32 s82, 0
	s_branch nap0_ydone
nap0_ygen:
	v_exp_f32_e32 v64, v80
	v_exp_f32_e32 v79, v81
	v_exp_f32_e32 v81, v82
	v_exp_f32_e32 v82, v83
	v_exp_f32_e32 v83, v84
	v_exp_f32_e32 v84, v85
	v_exp_f32_e32 v85, v86
	v_exp_f32_e32 v86, v87
	v_exp_f32_e32 v87, v88
	v_exp_f32_e32 v88, v89
	v_exp_f32_e32 v89, v90
	v_exp_f32_e32 v90, v91
	v_exp_f32_e32 v91, v92
	v_exp_f32_e32 v92, v93
	v_exp_f32_e32 v93, v94
	v_exp_f32_e32 v94, v95
	v_cvt_pk_bf16_f32 v80, v64, v79
	v_cvt_pk_bf16_f32 v81, v81, v82
	v_cvt_pk_bf16_f32 v82, v83, v84
	v_cvt_pk_bf16_f32 v83, v85, v86
	v_cvt_pk_bf16_f32 v84, v87, v88
	v_cvt_pk_bf16_f32 v85, v89, v90
	v_cvt_pk_bf16_f32 v86, v91, v92
	v_cvt_pk_bf16_f32 v87, v93, v94
	s_waitcnt lgkmcnt(6)
	v_mfma_f32_32x32x16_bf16 v[16:31], v[148:151], v[80:83], v[16:31]
	v_mov_b64_e32 v[90:91], s[86:87]
	v_mov_b64_e32 v[88:89], s[84:85]
	v_exp_f32_e32 v92, v206
	v_exp_f32_e32 v93, v65
	ds_read_b64_tr_b16 v[64:65], v238 offset:24576
	v_mfma_f32_32x32x16_bf16 v[32:47], v[88:91], v[80:83], v[32:47]
	v_exp_f32_e32 v94, v66
	v_exp_f32_e32 v95, v67
	v_exp_f32_e32 v96, v68
	v_exp_f32_e32 v97, v69
	ds_read_b64_tr_b16 v[66:67], v238 offset:26112
	ds_read_b64_tr_b16 v[68:69], v238 offset:24640
	s_waitcnt lgkmcnt(7)
	v_mfma_f32_32x32x16_bf16 v[0:15], v[144:147], v[80:83], v[0:15]
	v_exp_f32_e32 v98, v70
	v_exp_f32_e32 v99, v71
	v_exp_f32_e32 v100, v72
	v_exp_f32_e32 v101, v73
	ds_read_b64_tr_b16 v[70:71], v238 offset:26176
	ds_read_b64_tr_b16 v[72:73], v238 offset:27648
	v_mfma_f32_32x32x16_bf16 v[32:47], v[88:91], v[84:87], v[32:47]
	v_exp_f32_e32 v102, v74
	v_exp_f32_e32 v103, v75
	v_exp_f32_e32 v104, v76
	v_exp_f32_e32 v105, v77
	ds_read_b64_tr_b16 v[74:75], v238 offset:29184
	ds_read_b64_tr_b16 v[76:77], v238 offset:27712
	s_waitcnt lgkmcnt(9)
	v_mfma_f32_32x32x16_bf16 v[16:31], v[140:143], v[84:87], v[16:31]
	v_exp_f32_e32 v106, v78
	v_exp_f32_e32 v107, v161
	v_cvt_pk_bf16_f32 v80, v92, v93
	v_cvt_pk_bf16_f32 v81, v94, v95
	ds_read_b64_tr_b16 v[78:79], v238 offset:29248
	s_waitcnt lgkmcnt(8)
	v_mfma_f32_32x32x16_bf16 v[0:15], v[136:139], v[84:87], v[0:15]
	v_cvt_pk_bf16_f32 v82, v96, v97
	v_cvt_pk_bf16_f32 v83, v98, v99
	v_cvt_pk_bf16_f32 v84, v100, v101
	v_cvt_pk_bf16_f32 v85, v102, v103
	v_cvt_pk_bf16_f32 v86, v104, v105
	v_cvt_pk_bf16_f32 v87, v106, v107
	s_waitcnt lgkmcnt(6)
	v_mfma_f32_32x32x16_bf16 v[16:31], v[64:67], v[80:83], v[16:31]
	s_waitcnt lgkmcnt(4)
	v_mfma_f32_32x32x16_bf16 v[0:15], v[68:71], v[80:83], v[0:15]
	v_mfma_f32_32x32x16_bf16 v[32:47], v[88:91], v[80:83], v[32:47]
	s_waitcnt lgkmcnt(2)
	v_mfma_f32_32x32x16_bf16 v[16:31], v[72:75], v[84:87], v[16:31]
	s_waitcnt lgkmcnt(0)
	v_mfma_f32_32x32x16_bf16 v[0:15], v[76:79], v[84:87], v[0:15]
	v_mfma_f32_32x32x16_bf16 v[32:47], v[88:91], v[84:87], v[32:47]
	s_mov_b32 s82, 0
nap0_ydone:
.LBB0_162:
	s_andn2_b64 vcc, exec, s[90:91]
	s_cbranch_vccnz .LBB0_164
	s_and_b32 s8, s81, 1
	s_mul_i32 s9, s8, 0x2400
	v_add_u32_e32 v64, s9, v210
	s_mulk_i32 s8, 0x3000
	s_waitcnt vmcnt(1)
	ds_write_b128 v64, v[128:131]
	v_add_u32_e32 v64, s8, v211
	s_waitcnt vmcnt(0)
	ds_write_b128 v64, v[132:135] offset:18432

; #define LAS __attribute__((address_space(3)))
; template <int KIND> ...
;     ...
;             if (t + 1 < nt) ATT_LOAD(t + 1);
;             bool active = true;
;             if (KIND == 0 && t < n1) { const int kr = kr_lo + t; active = (kr >= rs_w) && (kr < rs_w + 8); }
;             if (__builtin_amdgcn_readfirstlane((int)active)) {
;                 const int buf = t & 1;
;                 bf16x8 kf[8];
; #pragma unroll
;                 for (int t4 = 0; t4 < 4; ++t4) { kf[2 * t4] = *(const LAS bf16x8*)(lds + buf * KBUF + koff + 32 * t4); kf[2 * t4 + 1] = *(const LAS bf16x8*)(lds + buf * KBUF + koff + 32 * KSTR + 32 * t4); }
;                 __builtin_amdgcn_sched_barrier(0);
;                 f32x16 s0, s1;
; #pragma unroll
;                 for (int t4 = 0; t4 < 4; ++t4) {
;                     s0 = __builtin_amdgcn_mfma_f32_32x32x16_bf16(kf[2 * t4], qf[t4], t4 == 0 ? mneg : s0, 0, 0, 0);
;                     s1 = __builtin_amdgcn_mfma_f32_32x32x16_bf16(kf[2 * t4 + 1], qf[t4], t4 == 0 ? mneg : s1, 0, 0, 0);
;                 }
;                 float ab0[16], ab1[16];
;                 const bool na_lat = (KIND == 0) && (t < n1);
;                 if (na_lat) {
;                     const int bo = boff0 + (kr_lo + t - qr + 7) * 124;
; #pragma unroll
;                     for (int j = 0; j < 16; ++j) {
;                         const int C0 = 8 * (j >> 2) + (j & 3), C1 = 32 + C0;
;                         const float b0 = *(const LAS float*)(lds + bo + 4 * C0), b1 = *(const LAS float*)(lds + bo + 4 * C1);
;                         ab0[j] = ((unsigned)(wb + C0) < 16u) ? b0 : -1e30f;
;                         ab1[j] = ((unsigned)(wb + C1) < 16u) ? b1 : -1e30f;
;                     }
; #pragma unroll
;                     for (int i = 0; i < 8; ++i) { __builtin_amdgcn_sched_group_barrier(0x008, 1, 0); __builtin_amdgcn_sched_group_barrier(0x100, 4, 0); __builtin_amdgcn_sched_group_barrier(0x002, 12, 0); }
;                 }
;                 __builtin_amdgcn_sched_barrier(0);
;                 s16x4 vfa[2][NDT][2], vfb[2][NDT][2];
; #pragma unroll
;                 for (int s = 0; s < 2; ++s)
; #pragma unroll
;                     for (int dt = 0; dt < NDT; ++dt) {
;                         vfa[s][dt][0] = __builtin_amdgcn_ds_read_tr16_b64_v4i16((LAS s16x4*)(lds + buf * VBUF + voff + (16 * s) * VSTR + 64 * dt));
nap1_145:
	s_add_i32 s81, s83, 1
	s_cmp_lt_i32 s81, s95
	s_cselect_b64 s[90:91], -1, 0
	s_cmp_ge_i32 s81, s95
	s_cbranch_scc1 nap1_147
	s_cmp_lt_i32 s81, s80
	s_cselect_b32 s8, s74, s77
	s_cselect_b32 s9, s5, s2
	s_add_i32 s8, s8, s83
	s_lshl_b32 s8, s8, 6
	s_add_i32 s8, s8, s9
	s_add_i32 s8, s8, 64
	v_add_u32_e32 v64, s8, v208
	s_movk_i32 s9, 0x1800
	v_mad_i64_i32 v[64:65], s[78:79], v64, s9, v[202:203]
	v_add_u32_e32 v66, s8, v209
	v_mad_i64_i32 v[66:67], s[78:79], v66, s9, v[204:205]
	global_load_dwordx4 v[128:131], v[64:65], off offset:2048
	global_load_dwordx4 v[132:135], v[66:67], off
nap1_147:
	s_cmp_lt_i32 s83, s80
	s_cselect_b64 s[78:79], -1, 0
	s_cmp_ge_i32 s83, s80
	s_cselect_b64 vcc, -1, 0
	s_add_i32 s10, s74, s83
	s_cmp_ge_i32 s10, s75
	s_cselect_b64 s[8:9], -1, 0
	s_cmp_lt_i32 s10, s76
	s_cselect_b64 s[10:11], -1, 0
	s_and_b64 s[8:9], s[8:9], s[10:11]
	s_or_b64 s[8:9], vcc, s[8:9]
	s_cmp_eq_u64 s[8:9], 0
	s_cbranch_scc1 nap1_162
	s_and_b32 s83, s83, 1
	s_mul_i32 s8, s83, 0x2400
	v_add_u32_e32 v68, s8, v212
	ds_read_b128 v[64:67], v68
	ds_read_b128 v[80:83], v68 offset:32
	ds_read_b128 v[84:87], v68 offset:4608
	ds_read_b128 v[88:91], v68 offset:4640
	ds_read_b128 v[92:95], v68 offset:64
	ds_read_b128 v[136:139], v68 offset:96
	ds_read_b128 v[140:143], v68 offset:4672
	ds_read_b128 v[144:147], v68 offset:4704
	s_waitcnt lgkmcnt(7)
	v_mfma_f32_32x32x16_bf16 v[96:111], v[64:67], v[112:115], v[48:63]
	s_andn2_b64 vcc, exec, s[78:79]
	s_waitcnt lgkmcnt(5)
	v_mfma_f32_32x32x16_bf16 v[64:79], v[84:87], v[112:115], v[48:63]
	v_mfma_f32_32x32x16_bf16 v[96:111], v[80:83], v[116:119], v[96:111]
	s_waitcnt lgkmcnt(4)
	v_mfma_f32_32x32x16_bf16 v[64:79], v[88:91], v[116:119], v[64:79]
	s_waitcnt lgkmcnt(3)
	v_mfma_f32_32x32x16_bf16 v[96:111], v[92:95], v[120:123], v[96:111]
	s_waitcnt lgkmcnt(1)
	v_mfma_f32_32x32x16_bf16 v[64:79], v[140:143], v[120:123], v[64:79]
	v_mfma_f32_32x32x16_bf16 v[96:111], v[136:139], v[124:127], v[96:111]
	s_waitcnt lgkmcnt(0)
	v_mfma_f32_32x32x16_bf16 v[64:79], v[144:147], v[124:127], v[64:79]
	s_cbranch_vccnz nap1_150
	ds_read2_b32 v[80:81], v237 offset0:32 offset1:33
	ds_read2_b32 v[86:87], v237 offset0:34 offset1:35
	v_readlane_b32 s8, v255, 33
	v_readlane_b32 s9, v255, 34
	s_waitcnt lgkmcnt(0)
	v_cndmask_b32_e64 v160, v229, v81, s[14:15]
	v_cndmask_b32_e64 v236, v229, v80, s[8:9]
	v_readlane_b32 s8, v255, 35
	v_readlane_b32 s9, v255, 36
	v_cndmask_b32_e64 v167, v229, v87, s[20:21]
	v_cndmask_b32_e64 v166, v229, v86, s[22:23]
	ds_read2_b32 v[82:83], v237 offset0:40 offset1:41
	ds_read2_b32 v[86:87], v237 offset0:42 offset1:43
	s_waitcnt lgkmcnt(0)
	v_cndmask_b32_e64 v169, v229, v83, s[28:29]
	v_cndmask_b32_e64 v168, v229, v82, s[30:31]
	v_cndmask_b32_e64 v173, v229, v87, s[38:39]
	v_cndmask_b32_e64 v172, v229, v86, s[40:41]
	ds_read2_b32 v[80:81], v237 offset0:48 offset1:49
	ds_read2_b32 v[86:87], v237 offset0:50 offset1:51
	s_waitcnt lgkmcnt(0)
	v_cndmask_b32_e64 v177, v229, v80, s[42:43]
	v_cndmask_b32_e64 v178, v229, v81, s[48:49]
	v_cndmask_b32_e64 v181, v229, v87, s[54:55]
	v_cndmask_b32_e64 v180, v229, v86, s[56:57]
	ds_read2_b32 v[80:81], v237 offset0:24 offset1:25
	ds_read2_b32 v[82:83], v237 offset0:56 offset1:57
	ds_read2_b32 v[84:85], v237 offset0:26 offset1:27
	ds_read2_b32 v[86:87], v237 offset0:58 offset1:59
	s_waitcnt lgkmcnt(0)
	v_cndmask_b32_e64 v189, v229, v81, s[58:59]
	v_cndmask_b32_e64 v188, v229, v80, s[60:61]
	v_cndmask_b32_e64 v187, v229, v83, s[62:63]
	v_cndmask_b32_e64 v186, v229, v82, s[64:65]
	v_cndmask_b32_e64 v201, v229, v85, s[66:67]
	v_cndmask_b32_e64 v200, v229, v84, s[68:69]
	v_cndmask_b32_e64 v191, v229, v87, s[70:71]
	v_cndmask_b32_e64 v190, v229, v86, s[72:73]
nap1_150:
	s_mulk_i32 s83, 0x3000
	v_add_u32_e32 v238, s83, v213
	ds_read_b64_tr_b16 v[148:149], v238 offset:18432
	ds_read_b64_tr_b16 v[150:151], v238 offset:19968
	ds_read_b64_tr_b16 v[146:147], v238 offset:20032
	ds_read_b64_tr_b16 v[144:145], v238 offset:18496
	ds_read_b64_tr_b16 v[140:141], v238 offset:21504
	ds_read_b64_tr_b16 v[142:143], v238 offset:23040
	ds_read_b64_tr_b16 v[138:139], v238 offset:23104
	ds_read_b64_tr_b16 v[136:137], v238 offset:21568
	s_and_b64 vcc, exec, s[78:79]
	s_cbranch_vccz nap1_152
	v_add_f32_e32 v65, v65, v160
	v_add_f32_e32 v66, v66, v166
	v_add_f32_e32 v67, v67, v167
	v_add_f32_e32 v68, v68, v168
	v_add_f32_e32 v69, v69, v169
	v_add_f32_e32 v70, v70, v172
	v_add_f32_e32 v71, v71, v173
	v_add_f32_e32 v72, v72, v177
	v_add_f32_e32 v73, v73, v178
	v_add_f32_e32 v74, v74, v180
	v_add_f32_e32 v75, v75, v181
	v_add_f32_e32 v76, v76, v186
	v_add_f32_e32 v77, v77, v187
	v_add_f32_e32 v78, v78, v190
	v_add_f32_e32 v206, v64, v236
	v_mov_b32_e32 v80, v229
	v_mov_b32_e32 v81, v229
	v_pk_add_f32 v[94:95], v[110:111], v[200:201]
	v_pk_add_f32 v[92:93], v[108:109], v[188:189]
	v_mov_b32_e32 v90, v229
	v_mov_b32_e32 v91, v229
	v_mov_b32_e32 v88, v229
	v_mov_b32_e32 v89, v229
	v_mov_b32_e32 v86, v229
	v_mov_b32_e32 v87, v229
	v_mov_b32_e32 v84, v229
	v_mov_b32_e32 v85, v229
	v_mov_b32_e32 v82, v229
	v_mov_b32_e32 v83, v229
	v_add_f32_e32 v161, v79, v191
	s_cbranch_execz nap1_153
	s_branch nap1_154
nap1_152:
nap1_153:
	v_mov_b64_e32 v[80:81], v[96:97]
	v_mov_b64_e32 v[82:83], v[98:99]
	v_mov_b64_e32 v[84:85], v[100:101]
	v_mov_b64_e32 v[86:87], v[102:103]
	v_mov_b64_e32 v[88:89], v[104:105]
	v_mov_b64_e32 v[90:91], v[106:107]
	v_mov_b64_e32 v[92:93], v[108:109]
	v_mov_b64_e32 v[94:95], v[110:111]
	v_mov_b32_e32 v206, v64
	v_mov_b32_e32 v161, v79
; __device__ __forceinline__ float max3f(float a, float b, float c) { float d; asm("v_max3_f32 %0, %1, %2, %3" : "=v"(d) : "v"(a), "v"(b), "v"(c)); return d; }
; template <int KIND> ...
;     ...
;                 const float mx0 = fmaxf(s1[15], s0[15]);
;                 float mxa = max3f(mx0, s0[0], s1[0]), mxb = max3f(mx0, s0[1], s1[1]);
; #pragma unroll
;                 for (int j = 2; j < 15; j += 2) { mxa = max3f(mxa, s0[j], s1[j]); mxb = max3f(mxb, s0[j + 1], s1[j + 1]); }
;                 float mx = fmaxf(mxa, mxb);
;                 if (first || __builtin_amdgcn_ballot_w64(mx > 8.0f) != 0ull) {
;                     mx = fmaxf(mx, __shfl_xor(mx, 32));
;                     const float d = first ? mx : fmaxf(mx, 0.f);
;                     const float alpha = first ? 1.0f : __builtin_amdgcn_exp2f(-d);
;                     m_ref += d;
; #pragma unroll
;                     for (int j = 0; j < 16; ++j) { mneg[j] -= d; s0[j] -= d; s1[j] -= d; lacc[j] *= alpha; }
; #pragma unroll
;                     for (int dt = 0; dt < NDT; ++dt)
; #pragma unroll
;                         for (int j = 0; j < 16; ++j) o[dt][j] *= alpha;
;                     first = 0;
;                 }
nap1_154:
	v_max_f32_e32 v64, v161, v161
	v_max_f32_e32 v79, v95, v95
	v_max_f32_e32 v64, v64, v79
	v_max3_f32 v79, v64, v80, v206
	v_max3_f32 v64, v64, v81, v65
	s_cmp_eq_u32 s82, 0
	v_max3_f32 v79, v79, v82, v66
	v_max3_f32 v64, v64, v83, v67
	s_cselect_b64 s[78:79], -1, 0
	v_max3_f32 v79, v79, v84, v68
	v_max3_f32 v64, v64, v85, v69
	s_and_b64 vcc, exec, s[78:79]
	v_max3_f32 v79, v79, v86, v70
	v_max3_f32 v64, v64, v87, v71
	s_nop 0
	v_max3_f32 v79, v79, v88, v72
	v_max3_f32 v64, v64, v89, v73
	s_nop 0
	v_max3_f32 v79, v79, v90, v74
	v_max3_f32 v64, v64, v91, v75
	s_nop 0
	v_max3_f32 v79, v79, v92, v76
	v_max3_f32 v96, v64, v93, v77
	s_nop 0
	v_max3_f32 v64, v79, v94, v78
	v_max3_f32 v79, v96, v95, v161
	s_cbranch_vccnz nap1_156
	s_mov_b64 vcc, 0
	s_mov_b64 s[82:83], -1
	s_branch nap1_157
nap1_156:
	s_mov_b64 vcc, -1
	s_mov_b64 s[82:83], 0
nap1_157:
	v_max_f32_e32 v79, v79, v79
	v_max_f32_e32 v64, v64, v64
	s_andn2_b64 vcc, exec, vcc
	v_max_f32_e32 v64, v64, v79
	s_cbranch_vccnz nap1_159
	s_mov_b32 s8, 0x41000000
	v_cmp_lt_f32_e32 vcc, s8, v64
	s_cmp_lg_u64 vcc, 0
	s_cselect_b64 s[82:83], -1, 0
nap1_159:
	s_andn2_b64 vcc, exec, s[82:83]
	s_cbranch_vccnz nap1_161
	ds_bpermute_b32 v96, v214, v64
	v_mov_b32_e32 v207, v65
	v_max_f32_e32 v64, v64, v64
	v_mov_b32_e32 v79, v161
	s_waitcnt lgkmcnt(0)
	v_max_f32_e32 v65, v96, v96
	v_max_f32_e32 v64, v64, v65
	v_max_f32_e32 v65, 0, v64
	v_cndmask_b32_e64 v64, v64, v65, s[78:79]
	v_exp_f32_e64 v65, -v64
	v_sub_f32_e32 v63, v63, v64
	v_sub_f32_e32 v62, v62, v64
	v_sub_f32_e32 v61, v61, v64
	v_pk_add_f32 v[206:207], v[206:207], v[64:65] op_sel_hi:[1,0] neg_lo:[0,1] neg_hi:[0,1]
	v_cndmask_b32_e64 v96, 1.0, v65, s[78:79]
	v_pk_add_f32 v[78:79], v[78:79], v[64:65] op_sel_hi:[1,0] neg_lo:[0,1] neg_hi:[0,1]
	v_pk_add_f32 v[80:81], v[80:81], v[64:65] op_sel_hi:[1,0] neg_lo:[0,1] neg_hi:[0,1]
	v_pk_add_f32 v[82:83], v[82:83], v[64:65] op_sel_hi:[1,0] neg_lo:[0,1] neg_hi:[0,1]
	v_pk_add_f32 v[66:67], v[66:67], v[64:65] op_sel_hi:[1,0] neg_lo:[0,1] neg_hi:[0,1]
	v_pk_add_f32 v[84:85], v[84:85], v[64:65] op_sel_hi:[1,0] neg_lo:[0,1] neg_hi:[0,1]
	v_pk_add_f32 v[68:69], v[68:69], v[64:65] op_sel_hi:[1,0] neg_lo:[0,1] neg_hi:[0,1]
	v_pk_add_f32 v[86:87], v[86:87], v[64:65] op_sel_hi:[1,0] neg_lo:[0,1] neg_hi:[0,1]
	v_pk_add_f32 v[70:71], v[70:71], v[64:65] op_sel_hi:[1,0] neg_lo:[0,1] neg_hi:[0,1]
	v_pk_add_f32 v[88:89], v[88:89], v[64:65] op_sel_hi:[1,0] neg_lo:[0,1] neg_hi:[0,1]
	v_pk_add_f32 v[72:73], v[72:73], v[64:65] op_sel_hi:[1,0] neg_lo:[0,1] neg_hi:[0,1]
	v_pk_add_f32 v[90:91], v[90:91], v[64:65] op_sel_hi:[1,0] neg_lo:[0,1] neg_hi:[0,1]
	v_pk_add_f32 v[74:75], v[74:75], v[64:65] op_sel_hi:[1,0] neg_lo:[0,1] neg_hi:[0,1]
	v_pk_add_f32 v[92:93], v[92:93], v[64:65] op_sel_hi:[1,0] neg_lo:[0,1] neg_hi:[0,1]
	v_pk_add_f32 v[76:77], v[76:77], v[64:65] op_sel_hi:[1,0] neg_lo:[0,1] neg_hi:[0,1]
	v_pk_add_f32 v[94:95], v[94:95], v[64:65] op_sel_hi:[1,0] neg_lo:[0,1] neg_hi:[0,1]
	v_pk_mul_f32 v[46:47], v[46:47], v[96:97] op_sel_hi:[1,0]
	v_pk_mul_f32 v[44:45], v[44:45], v[96:97] op_sel_hi:[1,0]
	v_pk_mul_f32 v[42:43], v[42:43], v[96:97] op_sel_hi:[1,0]
	v_pk_mul_f32 v[40:41], v[40:41], v[96:97] op_sel_hi:[1,0]
	v_pk_mul_f32 v[38:39], v[38:39], v[96:97] op_sel_hi:[1,0]
	v_pk_mul_f32 v[36:37], v[36:37], v[96:97] op_sel_hi:[1,0]
	v_pk_mul_f32 v[34:35], v[34:35], v[96:97] op_sel_hi:[1,0]
	v_pk_mul_f32 v[32:33], v[32:33], v[96:97] op_sel_hi:[1,0]
	v_pk_mul_f32 v[14:15], v[14:15], v[96:97] op_sel_hi:[1,0]
	v_pk_mul_f32 v[12:13], v[12:13], v[96:97] op_sel_hi:[1,0]
	v_pk_mul_f32 v[10:11], v[10:11], v[96:97] op_sel_hi:[1,0]
	v_pk_mul_f32 v[8:9], v[8:9], v[96:97] op_sel_hi:[1,0]
	v_pk_mul_f32 v[6:7], v[6:7], v[96:97] op_sel_hi:[1,0]
	v_pk_mul_f32 v[4:5], v[4:5], v[96:97] op_sel_hi:[1,0]
	v_pk_mul_f32 v[2:3], v[2:3], v[96:97] op_sel_hi:[1,0]
	v_pk_mul_f32 v[0:1], v[0:1], v[96:97] op_sel_hi:[1,0]
	v_pk_mul_f32 v[30:31], v[30:31], v[96:97] op_sel_hi:[1,0]
	v_pk_mul_f32 v[28:29], v[28:29], v[96:97] op_sel_hi:[1,0]
	v_pk_mul_f32 v[26:27], v[26:27], v[96:97] op_sel_hi:[1,0]
	v_pk_mul_f32 v[24:25], v[24:25], v[96:97] op_sel_hi:[1,0]
	v_pk_mul_f32 v[22:23], v[22:23], v[96:97] op_sel_hi:[1,0]
	v_pk_mul_f32 v[20:21], v[20:21], v[96:97] op_sel_hi:[1,0]
	v_pk_mul_f32 v[18:19], v[18:19], v[96:97] op_sel_hi:[1,0]
	v_pk_mul_f32 v[16:17], v[16:17], v[96:97] op_sel_hi:[1,0]
	v_sub_f32_e32 v60, v60, v64
	v_sub_f32_e32 v59, v59, v64
	v_sub_f32_e32 v58, v58, v64
	v_sub_f32_e32 v57, v57, v64
	v_sub_f32_e32 v56, v56, v64
	v_sub_f32_e32 v55, v55, v64
	v_sub_f32_e32 v54, v54, v64
	v_sub_f32_e32 v53, v53, v64
	v_sub_f32_e32 v52, v52, v64
	v_sub_f32_e32 v51, v51, v64
	v_sub_f32_e32 v50, v50, v64
	v_sub_f32_e32 v49, v49, v64
	v_sub_f32_e32 v48, v48, v64
	v_mov_b32_e32 v65, v207
	v_mov_b32_e32 v161, v79
; template <int KIND> ...
;     ...
; #pragma unroll
;                 for (int j = 0; j < 16; ++j) s0[j] = __builtin_amdgcn_exp2f(s0[j]);
;                 bf16x8 pf[4];
; #pragma unroll
;                 for (int s = 0; s < 2; ++s) { u32x4 w; w.x = pk2n(s0[8 * s + 0], s0[8 * s + 1]); w.y = pk2n(s0[8 * s + 2], s0[8 * s + 3]); w.z = pk2n(s0[8 * s + 4], s0[8 * s + 5]); w.w = pk2n(s0[8 * s + 6], s0[8 * s + 7]);
;                     pf[s] = __builtin_bit_cast(bf16x8, w); }
;                 __builtin_amdgcn_sched_barrier(0);
; #pragma unroll
;                 for (int s = 0; s < 2; ++s)
; #pragma unroll
;                     for (int dt = 0; dt < NDT; ++dt) {
;                         vfb[s][dt][0] = __builtin_amdgcn_ds_read_tr16_b64_v4i16((LAS s16x4*)(lds + buf * VBUF + voff + (16 * (s + 2)) * VSTR + 64 * dt));
;                         vfb[s][dt][1] = __builtin_amdgcn_ds_read_tr16_b64_v4i16((LAS s16x4*)(lds + buf * VBUF + voff + (16 * (s + 2) + 8) * VSTR + 64 * dt)); }
;                 {
;                     constexpr int NM = 2 * (1 + NDT);
;                     int mi = 0;
; #pragma unroll
;                     for (int s = 0; s < 2; ++s) {
;                         lacc = __builtin_amdgcn_mfma_f32_32x32x16_bf16(ones, pf[s], lacc, 0, 0, 0);
; #pragma unroll
;                         for (int j = (mi * 16) / NM; j < ((mi + 1) * 16) / NM; ++j) s1[j] = __builtin_amdgcn_exp2f(s1[j]);
;                         ++mi;
; #pragma unroll
;                         for (int dt = 0; dt < NDT; ++dt) {
;                             const s16x4 va = vfa[s][dt][0], vb = vfa[s][dt][1];
;                             const bf16x8 vf = {va[0], va[1], va[2], va[3], vb[0], vb[1], vb[2], vb[3]};
;                             o[dt] = __builtin_amdgcn_mfma_f32_32x32x16_bf16(vf, pf[s], o[dt], 0, 0, 0);
; #pragma unroll
;                             for (int j = (mi * 16) / NM; j < ((mi + 1) * 16) / NM; ++j) s1[j] = __builtin_amdgcn_exp2f(s1[j]);
;                             ++mi;
;                         }
;                     }
; #pragma unroll
;                     for (int q = 0; q < 2; ++q) { u32x4 w; w.x = pk2n(s1[8 * q + 0], s1[8 * q + 1]); w.y = pk2n(s1[8 * q + 2], s1[8 * q + 3]); w.z = pk2n(s1[8 * q + 4], s1[8 * q + 5]); w.w = pk2n(s1[8 * q + 6], s1[8 * q + 7]);
;                         pf[q + 2] = __builtin_bit_cast(bf16x8, w); }
; #pragma unroll
nap1_161:
	s_cmp_le_i32 s81, s80
	s_cbranch_scc0 nap1_ygen
	v_exp_f32_e32 v91, v92
	v_exp_f32_e32 v92, v93
	v_exp_f32_e32 v93, v94
	v_exp_f32_e32 v94, v95
	v_mov_b32_e32 v80, 0
	v_mov_b32_e32 v81, 0
	v_mov_b32_e32 v82, 0
	v_mov_b32_e32 v83, 0
	v_mov_b32_e32 v84, 0
	v_mov_b32_e32 v85, 0
	v_cvt_pk_bf16_f32 v86, v91, v92
	v_cvt_pk_bf16_f32 v87, v93, v94
	s_waitcnt lgkmcnt(6)
	v_mov_b64_e32 v[90:91], s[86:87]
	v_mov_b64_e32 v[88:89], s[84:85]
	v_exp_f32_e32 v92, v206
	v_exp_f32_e32 v93, v65
	ds_read_b64_tr_b16 v[64:65], v238 offset:24576
	v_exp_f32_e32 v94, v66
	v_exp_f32_e32 v95, v67
	v_exp_f32_e32 v96, v68
	v_exp_f32_e32 v97, v69
	ds_read_b64_tr_b16 v[66:67], v238 offset:26112
	ds_read_b64_tr_b16 v[68:69], v238 offset:24640
	s_waitcnt lgkmcnt(7)
	v_exp_f32_e32 v98, v70
	v_exp_f32_e32 v99, v71
	v_exp_f32_e32 v100, v72
	v_exp_f32_e32 v101, v73
	ds_read_b64_tr_b16 v[70:71], v238 offset:26176
	ds_read_b64_tr_b16 v[72:73], v238 offset:27648
	v_mfma_f32_32x32x16_bf16 v[32:47], v[88:91], v[84:87], v[32:47]
	v_exp_f32_e32 v102, v74
	v_exp_f32_e32 v103, v75
	v_exp_f32_e32 v104, v76
	v_exp_f32_e32 v105, v77
	ds_read_b64_tr_b16 v[74:75], v238 offset:29184
	ds_read_b64_tr_b16 v[76:77], v238 offset:27712
	s_waitcnt lgkmcnt(9)
	v_mfma_f32_32x32x16_bf16 v[16:31], v[140:143], v[84:87], v[16:31]
	v_exp_f32_e32 v106, v78
	v_exp_f32_e32 v107, v161
	v_cvt_pk_bf16_f32 v80, v92, v93
	v_cvt_pk_bf16_f32 v81, v94, v95
	ds_read_b64_tr_b16 v[78:79], v238 offset:29248
	s_waitcnt lgkmcnt(8)
	v_mfma_f32_32x32x16_bf16 v[0:15], v[136:139], v[84:87], v[0:15]
	v_cvt_pk_bf16_f32 v82, v96, v97
	v_cvt_pk_bf16_f32 v83, v98, v99
	v_cvt_pk_bf16_f32 v84, v100, v101
	v_cvt_pk_bf16_f32 v85, v102, v103
	v_cvt_pk_bf16_f32 v86, v104, v105
	v_cvt_pk_bf16_f32 v87, v106, v107
	s_waitcnt lgkmcnt(6)
	v_mfma_f32_32x32x16_bf16 v[16:31], v[64:67], v[80:83], v[16:31]
	s_waitcnt lgkmcnt(4)
	v_mfma_f32_32x32x16_bf16 v[0:15], v[68:71], v[80:83], v[0:15]
	v_mfma_f32_32x32x16_bf16 v[32:47], v[88:91], v[80:83], v[32:47]
	s_waitcnt lgkmcnt(2)
	v_mfma_f32_32x32x16_bf16 v[16:31], v[72:75], v[84:87], v[16:31]
	s_waitcnt lgkmcnt(0)
	v_mfma_f32_32x32x16_bf16 v[0:15], v[76:79], v[84:87], v[0:15]
	v_mfma_f32_32x32x16_bf16 v[32:47], v[88:91], v[84:87], v[32:47]
	s_mov_b32 s82, 0
	s_branch nap1_ydone
nap1_ygen:
	v_exp_f32_e32 v64, v80
	v_exp_f32_e32 v79, v81
	v_exp_f32_e32 v81, v82
	v_exp_f32_e32 v82, v83
	v_exp_f32_e32 v83, v84
	v_exp_f32_e32 v84, v85
	v_exp_f32_e32 v85, v86
	v_exp_f32_e32 v86, v87
	v_exp_f32_e32 v87, v88
	v_exp_f32_e32 v88, v89
	v_exp_f32_e32 v89, v90
	v_exp_f32_e32 v90, v91
	v_exp_f32_e32 v91, v92
	v_exp_f32_e32 v92, v93
	v_exp_f32_e32 v93, v94
	v_exp_f32_e32 v94, v95
	v_cvt_pk_bf16_f32 v80, v64, v79
	v_cvt_pk_bf16_f32 v81, v81, v82
	v_cvt_pk_bf16_f32 v82, v83, v84
	v_cvt_pk_bf16_f32 v83, v85, v86
	v_cvt_pk_bf16_f32 v84, v87, v88
	v_cvt_pk_bf16_f32 v85, v89, v90
	v_cvt_pk_bf16_f32 v86, v91, v92
	v_cvt_pk_bf16_f32 v87, v93, v94
	s_waitcnt lgkmcnt(6)
	v_mfma_f32_32x32x16_bf16 v[16:31], v[148:151], v[80:83], v[16:31]
	v_mov_b64_e32 v[90:91], s[86:87]
	v_mov_b64_e32 v[88:89], s[84:85]
	v_exp_f32_e32 v92, v206
	v_exp_f32_e32 v93, v65
	ds_read_b64_tr_b16 v[64:65], v238 offset:24576
	v_mfma_f32_32x32x16_bf16 v[32:47], v[88:91], v[80:83], v[32:47]
	v_exp_f32_e32 v94, v66
	v_exp_f32_e32 v95, v67
	v_exp_f32_e32 v96, v68
	v_exp_f32_e32 v97, v69
	ds_read_b64_tr_b16 v[66:67], v238 offset:26112
	ds_read_b64_tr_b16 v[68:69], v238 offset:24640
	s_waitcnt lgkmcnt(7)
	v_mfma_f32_32x32x16_bf16 v[0:15], v[144:147], v[80:83], v[0:15]
	v_exp_f32_e32 v98, v70
	v_exp_f32_e32 v99, v71
	v_exp_f32_e32 v100, v72
	v_exp_f32_e32 v101, v73
	ds_read_b64_tr_b16 v[70:71], v238 offset:26176
	ds_read_b64_tr_b16 v[72:73], v238 offset:27648
	v_mfma_f32_32x32x16_bf16 v[32:47], v[88:91], v[84:87], v[32:47]
	v_exp_f32_e32 v102, v74
	v_exp_f32_e32 v103, v75
	v_exp_f32_e32 v104, v76
	v_exp_f32_e32 v105, v77
	ds_read_b64_tr_b16 v[74:75], v238 offset:29184
	ds_read_b64_tr_b16 v[76:77], v238 offset:27712
	s_waitcnt lgkmcnt(9)
	v_mfma_f32_32x32x16_bf16 v[16:31], v[140:143], v[84:87], v[16:31]
	v_exp_f32_e32 v106, v78
	v_exp_f32_e32 v107, v161
	v_cvt_pk_bf16_f32 v80, v92, v93
	v_cvt_pk_bf16_f32 v81, v94, v95
	ds_read_b64_tr_b16 v[78:79], v238 offset:29248
	s_waitcnt lgkmcnt(8)
	v_mfma_f32_32x32x16_bf16 v[0:15], v[136:139], v[84:87], v[0:15]
	v_cvt_pk_bf16_f32 v82, v96, v97
	v_cvt_pk_bf16_f32 v83, v98, v99
	v_cvt_pk_bf16_f32 v84, v100, v101
	v_cvt_pk_bf16_f32 v85, v102, v103
	v_cvt_pk_bf16_f32 v86, v104, v105
	v_cvt_pk_bf16_f32 v87, v106, v107
	s_waitcnt lgkmcnt(6)
	v_mfma_f32_32x32x16_bf16 v[16:31], v[64:67], v[80:83], v[16:31]
	s_waitcnt lgkmcnt(4)
	v_mfma_f32_32x32x16_bf16 v[0:15], v[68:71], v[80:83], v[0:15]
	v_mfma_f32_32x32x16_bf16 v[32:47], v[88:91], v[80:83], v[32:47]
	s_waitcnt lgkmcnt(2)
	v_mfma_f32_32x32x16_bf16 v[16:31], v[72:75], v[84:87], v[16:31]
	s_waitcnt lgkmcnt(0)
	v_mfma_f32_32x32x16_bf16 v[0:15], v[76:79], v[84:87], v[0:15]
	v_mfma_f32_32x32x16_bf16 v[32:47], v[88:91], v[84:87], v[32:47]
	s_mov_b32 s82, 0
nap1_ydone:
nap1_162:
	s_andn2_b64 vcc, exec, s[90:91]
	s_cbranch_vccnz nap1_164
	s_and_b32 s8, s81, 1
	s_mul_i32 s9, s8, 0x2400
	v_add_u32_e32 v64, s9, v210
	s_mulk_i32 s8, 0x3000
	s_waitcnt vmcnt(1)
	ds_write_b128 v64, v[128:131]
	v_add_u32_e32 v64, s8, v211
	s_waitcnt vmcnt(0)
	ds_write_b128 v64, v[132:135] offset:18432
nap1_164:
	s_cmp_eq_u32 s95, s81
	v_add_u32_e32 v237, 0x7c, v237
	s_waitcnt lgkmcnt(0)
	s_barrier
	s_cbranch_scc1 .LBB0_125
	s_mov_b32 s83, s81
	s_branch nap1_145
